# P0: the 16 dt-column loads of every thread requested together instead of four serialized batches
# baseline (speedup 1.0000x reference)
; #define LAS __attribute__((address_space(3)))
; __global__ void __launch_bounds__(NTHR, 2) k_main(Args a) {
;     ...
;         for (int i = tid; i < 8 * 1024; i += NTHR) { const int h = i & 7, c = i >> 3; *(LAS float*)(ldsb + h * 16384 + 8448 + c * 4) = a.w_in[(size_t)c * PW + ODT + h]; }
.LBB0_14:
	s_or_b64 exec, exec, s[0:1]
	s_movk_i32 s0, 0x2000
	v_cmp_gt_i32_e32 vcc, s0, v2
	s_and_saveexec_b64 s[0:1], vcc
	s_cbranch_execz .LBB0_26
	v_and_b32_e32 v10, 7, v2
	v_lshl_add_u32 v1, v10, 14, 0
	v_readlane_b32 s20, v235, 4
	v_readlane_b32 s21, v235, 5
	v_lshrrev_b32_e32 v3, 3, v2
	v_mul_u32_u24_e32 v4, 0x2420, v3
	v_lshl_add_u32 v4, v10, 2, v4
	v_add_u32_e32 v4, 0x2400, v4
	v_lshl_add_u32 v5, v3, 2, v1
	s_nop 1
	global_load_dword v236, v4, s[20:21]
	v_add_u32_e32 v6, 0x90800, v4
	global_load_dword v237, v6, s[20:21]
	v_add_u32_e32 v6, 0x121000, v4
	global_load_dword v238, v6, s[20:21]
	v_add_u32_e32 v6, 0x1b1800, v4
	global_load_dword v239, v6, s[20:21]
	v_add_u32_e32 v6, 0x242000, v4
	global_load_dword v240, v6, s[20:21]
	v_add_u32_e32 v6, 0x2d2800, v4
	global_load_dword v241, v6, s[20:21]
	v_add_u32_e32 v6, 0x363000, v4
	global_load_dword v242, v6, s[20:21]
	v_add_u32_e32 v6, 0x3f3800, v4
	global_load_dword v243, v6, s[20:21]
	v_add_u32_e32 v6, 0x484000, v4
	global_load_dword v244, v6, s[20:21]
	v_add_u32_e32 v6, 0x514800, v4
	global_load_dword v245, v6, s[20:21]
	v_add_u32_e32 v6, 0x5a5000, v4
	global_load_dword v246, v6, s[20:21]
	v_add_u32_e32 v6, 0x635800, v4
	global_load_dword v247, v6, s[20:21]
	v_add_u32_e32 v6, 0x6c6000, v4
	global_load_dword v248, v6, s[20:21]
	v_add_u32_e32 v6, 0x756800, v4
	global_load_dword v249, v6, s[20:21]
	v_add_u32_e32 v6, 0x7e7000, v4
	global_load_dword v250, v6, s[20:21]
	v_add_u32_e32 v6, 0x877800, v4
	global_load_dword v251, v6, s[20:21]
	s_waitcnt vmcnt(0)
	ds_write_b32 v5, v236 offset:8448
	ds_write_b32 v5, v237 offset:8704
	ds_write_b32 v5, v238 offset:8960
	ds_write_b32 v5, v239 offset:9216
	ds_write_b32 v5, v240 offset:9472
	ds_write_b32 v5, v241 offset:9728
	ds_write_b32 v5, v242 offset:9984
	ds_write_b32 v5, v243 offset:10240
	ds_write_b32 v5, v244 offset:10496
	ds_write_b32 v5, v245 offset:10752
	ds_write_b32 v5, v246 offset:11008
	ds_write_b32 v5, v247 offset:11264
	ds_write_b32 v5, v248 offset:11520
	ds_write_b32 v5, v249 offset:11776
	ds_write_b32 v5, v250 offset:12032
	ds_write_b32 v5, v251 offset:12288

; __global__ void __launch_bounds__(NTHR, 2) k_main(Args a) {
;     ...
;         rmsnorm_rows_bf16<1>(a.x, a.norm_mix_g, XNB, ldsb, DTRAW, nullptr, RINV, gwave, nwaves, lane);
.LBB0_31:
	s_or_b64 exec, exec, s[10:11]
	s_nop 0
	s_nop 0
	s_nop 0
	s_nop 0
	s_nop 0
	s_nop 0
	s_nop 0
	s_nop 0
	s_nop 0
	s_nop 0
	s_nop 0
	s_nop 0
	s_nop 0
	s_nop 0
	s_nop 0
	s_nop 0
	s_nop 0
	s_nop 0
	s_nop 0
	s_nop 0
	s_nop 0
	s_nop 0
	s_nop 0
	s_nop 0
	s_nop 0
	s_nop 0
	s_nop 0
	s_nop 0
	s_nop 0
